# P3 dynamic queue: next unit's ticket requested at the start of the current unit's epilogue
# baseline (speedup 1.0000x reference)
; DI void phase3(const Params& p, unsigned char* smem, int tid, int cidx) {
;     ...
;     const int nun = (gridDim.x == 256) ? 1024 : 2048;
;     for (;;) {
;         if (tid == 0) sh[0] = (int)atomicAdd(ctr, 1u);
;         __syncthreads();
;         const int u = sh[0];
;         __syncthreads();
;         if (u >= nun) break;
;         int qi, type, bh;
;         if (gridDim.x == 256) { qi = 15 - (u >> 6); bh = u & 63; type = 1; }
;         else { qi = 15 - (u >> 7); const int rem = u & 127; type = rem & 1; bh = rem >> 1; }
;         const int b = bh >> 4, hd = bh & 15;
;         const size_t t0 = (size_t)b * L;
.LBB0_766:
	s_add_u32 s16, s54, 0x398fc00
	s_addc_u32 s17, s55, 0
	s_add_u32 s33, s54, 0x5a0fc00
	s_addc_u32 s50, s55, 0
	v_ashrrev_i32_e32 v2, 31, v136
	s_add_u32 s51, s54, 0xa7400
	v_lshrrev_b32_e32 v2, 29, v2
	s_addc_u32 s58, s55, 0
	s_movk_i32 s2, 0x200
	v_add_u32_e32 v2, v136, v2
	v_cmp_gt_i32_e64 s[6:7], s2, v136
	v_ashrrev_i32_e32 v147, 3, v2
	s_movk_i32 s2, 0x90
	s_add_u32 s59, s54, 0x7a8fc00
	v_lshlrev_b32_e32 v2, 6, v147
	v_mul_lo_u32 v168, v147, s2
	v_lshlrev_b32_e32 v6, 7, v147
	v_cmp_eq_u32_e64 s[10:11], 0, v0
	v_add_u32_e32 v0, 0, v185
	s_addc_u32 s84, s55, 0
	s_movk_i32 s2, 0x300
	v_sub_u32_e32 v150, v4, v2
	v_lshl_add_u64 v[4:5], s[54:55], 0, v[134:135]
	s_mov_b64 s[8:9], 0xab4fc00
	v_add_u32_e32 v2, 0, v168
	v_sub_u32_e32 v169, v3, v6
	v_lshl_add_u32 v172, v1, 2, 0
	v_add_u32_e32 v174, v0, v182
	v_add_u32_e32 v175, v0, v186
	s_add_u32 s85, s54, 0x9b0fc00
	v_cmp_gt_i32_e64 s[12:13], s2, v136
	s_movk_i32 s2, 0x100
	s_mov_b64 s[18:19], 0xcbcfc00
	v_add_u32_e32 v1, 0, v196
	v_add_u32_e32 v3, 0, v198
	v_sub_u32_e32 v0, v210, v165
	s_mov_b32 s65, 0
	v_cmp_eq_u32_e64 s[4:5], 0, v136
	v_ashrrev_i32_e32 v151, 31, v150
	v_lshl_add_u64 v[152:153], v[4:5], 0, s[8:9]
	v_cmp_gt_i32_e64 s[8:9], 64, v136
	v_add_u32_e32 v170, 0, v180
	v_lshlrev_b32_e32 v171, 2, v136
	v_mul_i32_i24_e32 v173, 0x90, v209
	s_addc_u32 s86, s55, 0
	v_cmp_gt_i32_e64 s[14:15], s2, v136
	v_lshl_add_u64 v[154:155], v[4:5], 0, s[18:19]
	v_subrev_u32_e32 v176, 64, v147
	v_subrev_u32_e32 v177, 64, v136
	v_add_u32_e32 v178, 0xf10, v0
	v_subrev_u32_e32 v179, 64, v184
	v_subrev_u32_e32 v202, 64, v189
	v_mov_b32_e32 v0, 0
	v_add_u32_e32 v203, v2, v169
	s_movk_i32 s87, 0x2c00
	v_mov_b32_e32 v204, 0x260
	v_mov_b32_e32 v205, 0x3c23d70a
	v_mov_b32_e32 v157, 0xc2200000
	s_add_i32 s88, 0, 0x9600
	s_movk_i32 s89, 0xc00
	v_add_u32_e32 v206, v1, v197
	v_add_u32_e32 v207, v3, v199
	s_movk_i32 s90, 0x3c00
	s_add_i32 s91, 0, 0xb600
	v_mov_b32_e32 v208, 0xff800000
	s_mov_b32 s98, 0
	s_branch .LBB0_771

; DI void phase3(const Params& p, unsigned char* smem, int tid, int cidx) {
;     ...
;     for (;;) {
;         if (tid == 0) sh[0] = (int)atomicAdd(ctr, 1u);
;         __syncthreads();
;         const int u = sh[0];
;         __syncthreads();
;         if (u >= nun) break;
.LBB0_771:
	s_and_saveexec_b64 s[18:19], s[4:5]
	s_cbranch_execz .LBB0_775
	s_mov_b64 s[22:23], exec
	v_mbcnt_lo_u32_b32 v1, s22, 0
	v_mbcnt_hi_u32_b32 v1, s23, v1
	v_cmp_eq_u32_e32 vcc, 0, v1
	s_and_saveexec_b64 s[20:21], vcc
	s_cbranch_execz .LBB0_774
	s_bcnt1_i32_b64 s2, s[22:23]
	s_cmp_lg_u32 s98, 0
	s_cbranch_scc1 .Lql_have
	v_mov_b32_e32 v2, s2
	global_atomic_add v2, v0, v2, s[54:55] sc0
	s_branch .Lql_done
.Lql_have:
	s_waitcnt vmcnt(0)
	v_mov_b32_e32 v2, v246
	s_mov_b32 s98, 0
.Lql_done:
.LBB0_774:
	s_or_b64 exec, exec, s[20:21]
	s_waitcnt vmcnt(0)
	v_readfirstlane_b32 s2, v2
	s_nop 1
	v_add_u32_e32 v1, s2, v1
	ds_write_b32 v0, v1

; DI u32x2 pk4(float a, float b, float c, float d) { u32x2 r; r.x = pk2(a, b); r.y = pk2(c, d); return r; }
;     ...
;     { const auto sw = __builtin_amdgcn_permlane32_swap(__float_as_uint(lsum), __float_as_uint(lsum), false, false);
;       lsum = __uint_as_float(sw[0]) + __uint_as_float(sw[1]); }
;     const float inv = 1.0f / lsum;
;     {
;         unsigned char* sb = lds + 2 * STG + wid * (32 * 144);
; #pragma unroll
;         for (int d = 0; d < 2; ++d)
; #pragma unroll
;             for (int g = 0; g < 4; ++g)
;                 *(u32x2*)(sb + ln * 144 + (d * 32 + 8 * g + 4 * h) * 2) = pk4(o[d][4 * g] * inv, o[d][4 * g + 1] * inv, o[d][4 * g + 2] * inv, o[d][4 * g + 3] * inv);
;         __builtin_amdgcn_fence(__ATOMIC_RELEASE, "wavefront");
;         __builtin_amdgcn_wave_barrier();
;         __builtin_amdgcn_fence(__ATOMIC_ACQUIRE, "wavefront");
; #pragma unroll
;         for (int ps = 0; ps < 4; ++ps) {
;             const int row = ps * 8 + (lane >> 3), ch = lane & 7;
;             const u32x4 v = *(const u32x4*)(sb + row * 144 + ch * 16);
;             *(u32x4*)(obase + (size_t)(qw0 + row) * ldo + ch * 8) = v;
;         }
; DI void phase3(const Params& p, unsigned char* smem, int tid, int cidx) {
;     ...
;         if (tid == 0) sh[0] = (int)atomicAdd(ctr, 1u);
.LBB0_821:
	s_and_saveexec_b64 s[100:101], s[4:5]
	s_cbranch_execz .Lql_skip
	v_mov_b32_e32 v246, 1
	global_atomic_add v246, v0, v246, s[54:55] sc0
	s_mov_b32 s98, 1
.Lql_skip:
	s_mov_b64 exec, s[100:101]
	v_mov_b32_e32 v1, v132
	s_nop 1
	v_permlane32_swap_b32_e32 v132, v1
	v_add_f32_e32 v1, v132, v1
	v_div_scale_f32 v2, s[18:19], v1, v1, 1.0
	v_rcp_f32_e32 v3, v2
	s_barrier
	v_fma_f32 v4, -v2, v3, 1.0
	v_fmac_f32_e32 v3, v4, v3
	v_div_scale_f32 v4, vcc, 1.0, v1, 1.0
	v_mul_f32_e32 v5, v4, v3
	v_fma_f32 v6, -v2, v5, v4
	v_fmac_f32_e32 v5, v6, v3
	v_fma_f32 v2, -v2, v5, v4
	v_div_fmas_f32 v2, v2, v3, v5
	v_div_fixup_f32 v2, v2, v1, 1.0
	v_pk_mul_f32 v[4:5], v[32:33], v[2:3] op_sel_hi:[1,0]
	v_pk_mul_f32 v[6:7], v[34:35], v[2:3] op_sel_hi:[1,0]
	v_cvt_pk_bf16_f32 v4, v4, v5
	v_cvt_pk_bf16_f32 v5, v6, v7
	v_add_u32_e32 v1, v174, v146
	v_pk_mul_f32 v[6:7], v[36:37], v[2:3] op_sel_hi:[1,0]
	v_pk_mul_f32 v[8:9], v[38:39], v[2:3] op_sel_hi:[1,0]
	v_cvt_pk_bf16_f32 v6, v6, v7
	v_cvt_pk_bf16_f32 v7, v8, v9
	v_add_u32_e32 v1, 0x9000, v1
	ds_write2_b64 v1, v[4:5], v[6:7] offset0:192 offset1:194
	v_pk_mul_f32 v[4:5], v[40:41], v[2:3] op_sel_hi:[1,0]
	v_pk_mul_f32 v[6:7], v[42:43], v[2:3] op_sel_hi:[1,0]
	v_cvt_pk_bf16_f32 v4, v4, v5
	v_cvt_pk_bf16_f32 v5, v6, v7
	v_pk_mul_f32 v[6:7], v[44:45], v[2:3] op_sel_hi:[1,0]
	v_pk_mul_f32 v[8:9], v[46:47], v[2:3] op_sel_hi:[1,0]
	v_cvt_pk_bf16_f32 v6, v6, v7
	v_cvt_pk_bf16_f32 v7, v8, v9
	ds_write2_b64 v1, v[4:5], v[6:7] offset0:196 offset1:198
	v_pk_mul_f32 v[4:5], v[16:17], v[2:3] op_sel_hi:[1,0]
	v_pk_mul_f32 v[6:7], v[18:19], v[2:3] op_sel_hi:[1,0]
	v_cvt_pk_bf16_f32 v4, v4, v5
	v_cvt_pk_bf16_f32 v5, v6, v7
	v_pk_mul_f32 v[6:7], v[20:21], v[2:3] op_sel_hi:[1,0]
	v_pk_mul_f32 v[8:9], v[22:23], v[2:3] op_sel_hi:[1,0]
	v_cvt_pk_bf16_f32 v6, v6, v7
	v_cvt_pk_bf16_f32 v7, v8, v9
	ds_write2_b64 v1, v[4:5], v[6:7] offset0:200 offset1:202
	v_pk_mul_f32 v[4:5], v[24:25], v[2:3] op_sel_hi:[1,0]
	v_pk_mul_f32 v[6:7], v[26:27], v[2:3] op_sel_hi:[1,0]
	v_cvt_pk_bf16_f32 v4, v4, v5
	v_cvt_pk_bf16_f32 v5, v6, v7
	v_pk_mul_f32 v[6:7], v[28:29], v[2:3] op_sel_hi:[1,0]
	v_pk_mul_f32 v[2:3], v[30:31], v[2:3] op_sel_hi:[1,0]
	v_cvt_pk_bf16_f32 v6, v6, v7
	v_cvt_pk_bf16_f32 v7, v2, v3
	ds_write2_b64 v1, v[4:5], v[6:7] offset0:204 offset1:206
	v_add_u32_e32 v1, v175, v187
	ds_read_b128 v[2:5], v1 offset:38400
	v_or_b32_e32 v8, v209, v167
	v_ashrrev_i32_e32 v9, 31, v8
	v_lshl_add_u64 v[6:7], v[142:143], 1, s[68:69]
	v_lshlrev_b64 v[8:9], 11, v[8:9]
	v_lshl_add_u64 v[6:7], v[6:7], 0, v[8:9]
	s_mov_b64 s[18:19], 0
	s_waitcnt lgkmcnt(0)
	global_store_dwordx4 v[6:7], v[2:5], off
